# plus: dilated attention issues next item's K/Q loads right after the K-free barrier (code motion)
# speedup vs baseline: 1.0130x; 1.0005x over previous
.LBB0_1085:
	v_max3_f32 v18, v93, s58, v88
	v_max3_f32 v18, v18, v77, v76
	v_max3_f32 v18, v18, v79, v78
	v_max3_f32 v18, v18, v73, v72
	v_max3_f32 v18, v18, v75, v74
	v_max3_f32 v18, v18, v69, v68
	v_max3_f32 v18, v18, v71, v70
	v_max3_f32 v18, v18, v65, v64
	v_max3_f32 v18, v18, v67, v66
	v_max3_f32 v18, v18, v61, v60
	v_max3_f32 v18, v18, v63, v62
	v_max3_f32 v18, v18, v57, v56
	v_max3_f32 v18, v18, v59, v58
	v_max3_f32 v18, v18, v177, v53
	v_max3_f32 v18, v18, v55, v54
	v_max3_f32 v18, v18, v49, v48
	v_max3_f32 v18, v18, v51, v50
	v_max3_f32 v18, v18, v45, v44
	v_max3_f32 v18, v18, v47, v46
	v_max3_f32 v18, v18, v41, v40
	v_max3_f32 v18, v18, v43, v42
	v_max3_f32 v18, v18, v37, v36
	v_max3_f32 v18, v18, v39, v38
	v_max3_f32 v18, v18, v33, v32
	v_max3_f32 v18, v18, v35, v34
	v_max3_f32 v18, v18, v29, v28
	v_max3_f32 v18, v18, v31, v30
	v_max3_f32 v18, v18, v25, v24
	v_and_b32_e32 v52, 64, v175
	v_max3_f32 v18, v18, v27, v26
	v_xor_b32_e32 v19, 16, v175
	v_add_u32_e32 v52, 64, v52
	v_max3_f32 v18, v18, v21, v20
	v_cmp_lt_i32_e32 vcc, v19, v52
	v_max3_f32 v18, v18, v23, v22
	v_max3_f32 v18, v18, v17, v16
	v_cndmask_b32_e32 v19, v175, v19, vcc
	v_lshlrev_b32_e32 v19, 2, v19
	ds_bpermute_b32 v95, v19, v18
	s_waitcnt vmcnt(0) lgkmcnt(0)
	s_add_i32 s22, s66, s77
	s_barrier
	s_cmpk_gt_i32 s22, 0xbff
	s_cselect_b64 s[12:13], -1, 0
	s_and_b64 vcc, exec, s[12:13]
	s_cbranch_vccnz .Lk_early_skip
	s_mov_b32 s18, s22
	s_ashr_i32 s20, s18, 4
	s_mul_hi_i32 s0, s20, 0x55555556
	s_lshr_b32 s1, s0, 31
	s_add_i32 s21, s0, s1
	s_mul_i32 s0, s21, 3
	s_and_b32 s19, s18, 15
	s_sub_i32 s23, s20, s0
	s_cmp_eq_u32 s23, 0
	s_cselect_b64 s[0:1], -1, 0
	s_cmp_eq_u32 s23, 1
	s_cselect_b64 s[14:15], -1, 0
	s_bfe_u32 s24, s18, 0x20002
	s_and_b64 s[16:17], s[14:15], exec
	s_cselect_b32 s24, s24, s19
	s_and_b64 s[16:17], s[0:1], exec
	s_cselect_b32 s24, 0, s24
	s_and_b32 s18, s18, 3
	s_and_b64 s[16:17], s[14:15], exec
	s_cselect_b32 s18, s18, 0
	s_and_b64 s[16:17], s[0:1], exec
	s_mul_hi_i32 s16, s20, 0x2aaaaaab
	s_cselect_b32 s25, s19, s18
	s_lshr_b32 s17, s16, 31
	s_ashr_i32 s16, s16, 2
	s_add_i32 s16, s16, s17
	s_and_b64 s[18:19], s[14:15], exec
	s_cselect_b32 s17, s54, 0x28000
	s_and_b64 s[18:19], s[0:1], exec
	s_cselect_b32 s20, 0x2800, s17
	s_ashr_i32 s17, s16, 31
	s_lshl_b64 s[16:17], s[16:17], 11
	s_lshl_b32 s26, s25, 7
	s_and_b64 s[18:19], s[14:15], exec
	s_cselect_b32 s27, 2, 4
	s_and_b64 s[18:19], s[0:1], exec
	s_cselect_b32 s18, 0, s27
	s_lshl_b32 s18, s26, s18
	s_add_u32 s16, s16, s18
	s_addc_u32 s17, s17, 0
	s_or_b32 s16, s16, s24
	s_mulk_i32 s17, 0x5000
	s_mul_hi_u32 s18, s16, 0x5000
	s_add_i32 s18, s18, s17
	s_mulk_i32 s16, 0x5000
	s_add_u32 s19, s48, s16
	s_addc_u32 s18, s49, s18
	s_lshl_b32 s16, s23, 10
	s_ashr_i32 s17, s16, 31
	s_lshl_b64 s[16:17], s[16:17], 1
	s_add_u32 s16, s19, s16
	s_addc_u32 s17, s18, s17
	s_lshl_b32 s18, s21, 8
	s_and_b32 s18, s18, 0x700
	s_add_u32 s16, s16, s18
	s_addc_u32 s17, s17, 0
	s_and_b64 s[14:15], s[14:15], exec
	s_cselect_b32 s14, s55, 0xfd800000
	s_and_b64 s[0:1], s[0:1], exec
	s_cselect_b32 s0, 0xffd80000, s14
	s_add_u32 s0, s16, s0
	s_addc_u32 s1, s17, -1
	s_cmp_eq_u32 s25, 0
	s_mov_b32 s14, s81
	s_cselect_b32 s18, 0x80, 0
	s_lshl_b32 s14, s14, 10
	v_max_i32_e32 v0, s18, v96
	s_add_i32 s19, s14, 0
	v_mad_u64_u32 v[0:1], s[14:15], s20, v0, 0
	v_max_i32_e32 v2, s18, v98
	v_lshl_add_u64 v[0:1], v[0:1], 1, s[0:1]
	v_mad_u64_u32 v[2:3], s[14:15], s20, v2, 0
	v_lshl_add_u64 v[0:1], v[0:1], 0, v[82:83]
	s_mov_b32 m0, s19
	v_lshl_add_u64 v[2:3], v[2:3], 1, s[0:1]
	global_load_lds_dwordx4 v[0:1], off
	v_lshl_add_u64 v[2:3], v[2:3], 0, v[84:85]
	s_add_i32 m0, s19, 0x2000
	v_lshl_add_u64 v[0:1], v[0:1], 0, s[8:9]
	global_load_lds_dwordx4 v[2:3], off
	s_add_i32 m0, s19, 0x4000
	v_mov_b32_e32 v104, v92
	v_mov_b32_e32 v105, v89
	global_load_lds_dwordx4 v[0:1], off
	v_lshl_add_u64 v[0:1], v[2:3], 0, s[8:9]
	s_add_i32 m0, s19, 0x6000
	v_max_i32_e32 v2, s18, v101
	global_load_lds_dwordx4 v[0:1], off
	v_max_i32_e32 v0, s18, v100
	v_mad_u64_u32 v[0:1], s[14:15], s20, v0, 0
	v_lshl_add_u64 v[0:1], v[0:1], 1, s[0:1]
	v_mad_u64_u32 v[2:3], s[14:15], s20, v2, 0
	s_add_i32 m0, s19, 0x8000
	v_lshl_add_u64 v[0:1], v[0:1], 0, v[82:83]
	v_lshl_add_u64 v[2:3], v[2:3], 1, s[0:1]
	global_load_lds_dwordx4 v[0:1], off
	v_lshl_add_u64 v[2:3], v[2:3], 0, v[84:85]
	s_add_i32 m0, s19, 0xa000
	v_lshl_add_u64 v[0:1], v[0:1], 0, s[8:9]
	global_load_lds_dwordx4 v[2:3], off
	s_add_i32 m0, s19, 0xc000
	s_nop 0
	global_load_lds_dwordx4 v[0:1], off
	v_lshl_add_u64 v[0:1], v[2:3], 0, s[8:9]
	s_add_i32 m0, s19, 0xe000
	s_nop 0
	global_load_lds_dwordx4 v[0:1], off
	v_mad_u64_u32 v[0:1], s[0:1], s20, v86, 0
	v_lshl_add_u64 v[0:1], v[0:1], 1, s[16:17]
	v_lshl_add_u64 v[0:1], v[0:1], 0, v[104:105]
	v_add_co_u32_e32 v8, vcc, 0x3000, v0
	v_lshl_add_u64 v[12:13], v[0:1], 0, s[10:11]
	s_nop 0
	v_addc_co_u32_e32 v9, vcc, 0, v1, vcc
	global_load_dwordx4 v[0:3], v[12:13], off offset:64
	global_load_dwordx4 v[4:7], v[12:13], off offset:128
	s_nop 0
	global_load_dwordx4 v[8:11], v[8:9], off
	s_nop 0
	global_load_dwordx4 v[12:15], v[12:13], off offset:192
.Lk_early_skip:
	s_waitcnt lgkmcnt(0)
	v_max_f32_e32 v95, v95, v95
	v_max_f32_e32 v18, v18, v95
	v_xor_b32_e32 v95, 32, v175
	v_cmp_lt_i32_e32 vcc, v95, v52
	s_cmpk_gt_i32 s22, 0xbff
	s_cselect_b64 s[12:13], -1, 0
	v_cndmask_b32_e32 v52, v175, v95, vcc
	v_lshlrev_b32_e32 v214, 2, v52
	ds_bpermute_b32 v52, v214, v18
	v_cmp_lt_f32_e32 vcc, s59, v77
	s_waitcnt lgkmcnt(0)
	v_max_f32_e32 v52, v52, v52
	v_max_f32_e32 v52, v18, v52
	v_sub_f32_e32 v198, v57, v52
	v_mul_f32_e32 v198, 0x3fb8aa3b, v198
	v_exp_f32_e32 v215, v198
	v_sub_f32_e32 v198, v56, v52
	v_mul_f32_e32 v198, 0x3fb8aa3b, v198
	v_exp_f32_e32 v216, v198
	v_sub_f32_e32 v198, v59, v52
	v_mul_f32_e32 v198, 0x3fb8aa3b, v198
	v_exp_f32_e32 v217, v198
	v_sub_f32_e32 v198, v58, v52
	v_mul_f32_e32 v198, 0x3fb8aa3b, v198
	v_exp_f32_e32 v218, v198
	v_sub_f32_e32 v198, v177, v52
	v_mul_f32_e32 v198, 0x3fb8aa3b, v198
	v_exp_f32_e32 v219, v198
	v_sub_f32_e32 v198, v53, v52
	v_mul_f32_e32 v198, 0x3fb8aa3b, v198
	v_exp_f32_e32 v220, v198
	v_sub_f32_e32 v198, v55, v52
	v_mul_f32_e32 v198, 0x3fb8aa3b, v198
	v_exp_f32_e32 v221, v198
	v_sub_f32_e32 v198, v54, v52
	v_mul_f32_e32 v198, 0x3fb8aa3b, v198
	v_exp_f32_e32 v222, v198
	v_sub_f32_e32 v198, v49, v52
	v_mul_f32_e32 v198, 0x3fb8aa3b, v198
	v_exp_f32_e32 v223, v198
	v_sub_f32_e32 v198, v48, v52
	v_mul_f32_e32 v198, 0x3fb8aa3b, v198
	v_exp_f32_e32 v224, v198
	v_sub_f32_e32 v198, v51, v52
	v_mul_f32_e32 v198, 0x3fb8aa3b, v198
	v_exp_f32_e32 v225, v198
	v_sub_f32_e32 v198, v50, v52
	v_mul_f32_e32 v198, 0x3fb8aa3b, v198
	v_exp_f32_e32 v226, v198
	v_sub_f32_e32 v198, v45, v52
	v_mul_f32_e32 v198, 0x3fb8aa3b, v198
	v_exp_f32_e32 v227, v198
	v_sub_f32_e32 v198, v44, v52
	v_mul_f32_e32 v198, 0x3fb8aa3b, v198
	v_exp_f32_e32 v228, v198
	v_sub_f32_e32 v198, v47, v52
	v_mul_f32_e32 v198, 0x3fb8aa3b, v198
	v_exp_f32_e32 v229, v198
	v_sub_f32_e32 v198, v46, v52
	v_mul_f32_e32 v198, 0x3fb8aa3b, v198
	v_exp_f32_e32 v230, v198
	v_sub_f32_e32 v198, v41, v52
	v_mul_f32_e32 v198, 0x3fb8aa3b, v198
	v_exp_f32_e32 v231, v198
	v_sub_f32_e32 v198, v40, v52
	v_mul_f32_e32 v198, 0x3fb8aa3b, v198
	v_exp_f32_e32 v232, v198
	v_sub_f32_e32 v198, v43, v52
	v_mul_f32_e32 v198, 0x3fb8aa3b, v198
	v_exp_f32_e32 v233, v198
	v_sub_f32_e32 v198, v42, v52
	v_mul_f32_e32 v198, 0x3fb8aa3b, v198
	v_exp_f32_e32 v234, v198
	v_sub_f32_e32 v198, v37, v52
	v_mul_f32_e32 v198, 0x3fb8aa3b, v198
	v_exp_f32_e32 v235, v198
	v_sub_f32_e32 v198, v36, v52
	v_mul_f32_e32 v198, 0x3fb8aa3b, v198
	v_exp_f32_e32 v236, v198
	v_sub_f32_e32 v198, v39, v52
	v_mul_f32_e32 v198, 0x3fb8aa3b, v198
	v_exp_f32_e32 v237, v198
	v_sub_f32_e32 v198, v38, v52
	v_mul_f32_e32 v198, 0x3fb8aa3b, v198
	v_exp_f32_e32 v238, v198
	v_sub_f32_e32 v198, v33, v52
	v_mul_f32_e32 v198, 0x3fb8aa3b, v198
	v_exp_f32_e32 v239, v198
	v_sub_f32_e32 v198, v32, v52
	v_mul_f32_e32 v198, 0x3fb8aa3b, v198
	v_exp_f32_e32 v240, v198
	v_sub_f32_e32 v198, v35, v52
	v_mul_f32_e32 v198, 0x3fb8aa3b, v198
	v_exp_f32_e32 v241, v198
	v_sub_f32_e32 v198, v34, v52
	v_mul_f32_e32 v198, 0x3fb8aa3b, v198
	v_exp_f32_e32 v242, v198
	v_sub_f32_e32 v198, v29, v52
	v_mul_f32_e32 v198, 0x3fb8aa3b, v198
	v_exp_f32_e32 v243, v198
	v_sub_f32_e32 v198, v28, v52
	v_mul_f32_e32 v198, 0x3fb8aa3b, v198
	v_exp_f32_e32 v244, v198
	v_sub_f32_e32 v198, v31, v52
	v_mul_f32_e32 v198, 0x3fb8aa3b, v198
	v_exp_f32_e32 v245, v198
	v_sub_f32_e32 v198, v30, v52
	v_mul_f32_e32 v198, 0x3fb8aa3b, v198
	v_exp_f32_e32 v246, v198
	v_sub_f32_e32 v198, v25, v52
	v_mul_f32_e32 v198, 0x3fb8aa3b, v198
	v_exp_f32_e32 v247, v198
	v_sub_f32_e32 v198, v24, v52
	v_mul_f32_e32 v198, 0x3fb8aa3b, v198
	v_exp_f32_e32 v248, v198
	v_sub_f32_e32 v198, v27, v52
	v_mul_f32_e32 v198, 0x3fb8aa3b, v198
	v_sub_f32_e32 v178, v77, v52
	v_exp_f32_e32 v249, v198
	v_sub_f32_e32 v198, v26, v52
	v_sub_f32_e32 v18, v93, v52
	v_mul_f32_e32 v178, 0x3fb8aa3b, v178
	v_mul_f32_e32 v198, 0x3fb8aa3b, v198
	v_mul_f32_e32 v18, 0x3fb8aa3b, v18
	v_exp_f32_e32 v178, v178
	v_sub_f32_e32 v179, v76, v52
	v_exp_f32_e32 v250, v198
	v_sub_f32_e32 v198, v21, v52
	v_exp_f32_e32 v18, v18
	v_sub_f32_e32 v95, v88, v52
	v_mul_f32_e32 v179, 0x3fb8aa3b, v179
	v_mul_f32_e32 v198, 0x3fb8aa3b, v198
	v_mul_f32_e32 v95, 0x3fb8aa3b, v95
	v_exp_f32_e32 v179, v179
	v_sub_f32_e32 v182, v73, v52
	v_exp_f32_e32 v251, v198
	v_sub_f32_e32 v198, v20, v52
	v_exp_f32_e32 v95, v95
	v_sub_f32_e32 v180, v79, v52
	v_mul_f32_e32 v182, 0x3fb8aa3b, v182
	v_mul_f32_e32 v198, 0x3fb8aa3b, v198
	v_mul_f32_e32 v180, 0x3fb8aa3b, v180
	v_exp_f32_e32 v182, v182
	v_sub_f32_e32 v183, v72, v52
	v_exp_f32_e32 v252, v198
	v_sub_f32_e32 v198, v23, v52
	v_cndmask_b32_e32 v206, 0, v178, vcc
	v_cmp_lt_f32_e32 vcc, s59, v93
	v_exp_f32_e32 v180, v180
	v_sub_f32_e32 v181, v78, v52
	v_mul_f32_e32 v183, 0x3fb8aa3b, v183
	v_mul_f32_e32 v198, 0x3fb8aa3b, v198
	v_cndmask_b32_e32 v207, 0, v18, vcc
	v_cmp_lt_f32_e32 vcc, s59, v76
	v_mul_f32_e32 v181, 0x3fb8aa3b, v181
	v_exp_f32_e32 v183, v183
	v_sub_f32_e32 v186, v69, v52
	v_exp_f32_e32 v253, v198
	v_sub_f32_e32 v198, v22, v52
	v_cndmask_b32_e32 v208, 0, v179, vcc
	v_cmp_lt_f32_e32 vcc, s59, v88
	v_exp_f32_e32 v181, v181
	v_sub_f32_e32 v184, v75, v52
	v_mul_f32_e32 v186, 0x3fb8aa3b, v186
	v_mul_f32_e32 v198, 0x3fb8aa3b, v198
	v_add_f32_e32 v18, 0, v207
	v_cndmask_b32_e32 v211, 0, v95, vcc
	v_cmp_lt_f32_e32 vcc, s59, v73
	v_mul_f32_e32 v184, 0x3fb8aa3b, v184
	v_exp_f32_e32 v186, v186
	v_sub_f32_e32 v187, v68, v52
	v_exp_f32_e32 v254, v198
	v_sub_f32_e32 v198, v17, v52
	v_add_f32_e32 v18, v211, v18
	v_cndmask_b32_e32 v209, 0, v182, vcc
	v_cmp_lt_f32_e32 vcc, s59, v79
	v_exp_f32_e32 v184, v184
	v_sub_f32_e32 v185, v74, v52
	v_mul_f32_e32 v187, 0x3fb8aa3b, v187
	v_mul_f32_e32 v198, 0x3fb8aa3b, v198
	v_add_f32_e32 v18, v206, v18
	v_cndmask_b32_e32 v210, 0, v180, vcc
	v_cmp_lt_f32_e32 vcc, s59, v72
	v_mul_f32_e32 v185, 0x3fb8aa3b, v185
	v_exp_f32_e32 v187, v187
	v_sub_f32_e32 v190, v65, v52
	v_exp_f32_e32 v135, v198
	v_sub_f32_e32 v198, v16, v52
	v_add_f32_e32 v18, v208, v18
	v_cndmask_b32_e32 v212, 0, v183, vcc
	v_cmp_lt_f32_e32 vcc, s59, v78
	v_exp_f32_e32 v185, v185
	v_sub_f32_e32 v188, v71, v52
	v_mul_f32_e32 v190, 0x3fb8aa3b, v190
	v_mul_f32_e32 v198, 0x3fb8aa3b, v198
	v_cndmask_b32_e32 v213, 0, v181, vcc
	v_add_f32_e32 v18, v210, v18
	v_cmp_lt_f32_e32 vcc, s59, v69
	v_mul_f32_e32 v188, 0x3fb8aa3b, v188
	v_exp_f32_e32 v190, v190
	v_sub_f32_e32 v191, v64, v52
	v_exp_f32_e32 v176, v198
	v_add_f32_e32 v18, v213, v18
	v_cndmask_b32_e32 v198, 0, v186, vcc
	v_cmp_lt_f32_e32 vcc, s59, v75
	v_exp_f32_e32 v188, v188
	v_sub_f32_e32 v189, v70, v52
	v_mul_f32_e32 v191, 0x3fb8aa3b, v191
	v_add_f32_e32 v18, v209, v18
	v_cndmask_b32_e32 v199, 0, v184, vcc
	v_cmp_lt_f32_e32 vcc, s59, v68
	v_mul_f32_e32 v189, 0x3fb8aa3b, v189
	v_exp_f32_e32 v191, v191
	v_sub_f32_e32 v194, v61, v52
	v_add_f32_e32 v18, v212, v18
	v_cndmask_b32_e32 v200, 0, v187, vcc
	v_cmp_lt_f32_e32 vcc, s59, v74
	v_exp_f32_e32 v189, v189
	v_sub_f32_e32 v192, v67, v52
	v_mul_f32_e32 v194, 0x3fb8aa3b, v194
	v_add_f32_e32 v18, v199, v18
	v_cndmask_b32_e32 v203, 0, v185, vcc
	v_cmp_lt_f32_e32 vcc, s59, v65
	v_mul_f32_e32 v192, 0x3fb8aa3b, v192
	v_exp_f32_e32 v194, v194
	v_sub_f32_e32 v195, v60, v52
	v_add_f32_e32 v18, v203, v18
	v_cndmask_b32_e32 v201, 0, v190, vcc
	v_cmp_lt_f32_e32 vcc, s59, v71
	v_exp_f32_e32 v192, v192
	v_sub_f32_e32 v193, v66, v52
	v_mul_f32_e32 v195, 0x3fb8aa3b, v195
	v_add_f32_e32 v18, v198, v18
	v_cndmask_b32_e32 v202, 0, v188, vcc
	v_cmp_lt_f32_e32 vcc, s59, v64
	v_mul_f32_e32 v193, 0x3fb8aa3b, v193
	v_exp_f32_e32 v195, v195
	v_add_f32_e32 v18, v200, v18
	v_cndmask_b32_e32 v204, 0, v191, vcc
	v_cmp_lt_f32_e32 vcc, s59, v70
	v_exp_f32_e32 v193, v193
	v_sub_f32_e32 v196, v63, v52
	v_cndmask_b32_e32 v205, 0, v189, vcc
	v_add_f32_e32 v18, v202, v18
	v_cmp_lt_f32_e32 vcc, s59, v61
	v_mul_f32_e32 v196, 0x3fb8aa3b, v196
	v_add_f32_e32 v18, v205, v18
	v_cndmask_b32_e32 v190, 0, v194, vcc
	v_cmp_lt_f32_e32 vcc, s59, v67
	v_exp_f32_e32 v196, v196
	v_sub_f32_e32 v197, v62, v52
	v_add_f32_e32 v18, v201, v18
	v_cndmask_b32_e32 v191, 0, v192, vcc
	v_cmp_lt_f32_e32 vcc, s59, v60
	v_mul_f32_e32 v197, 0x3fb8aa3b, v197
	v_add_f32_e32 v18, v204, v18
	v_cndmask_b32_e32 v192, 0, v195, vcc
	v_cmp_lt_f32_e32 vcc, s59, v66
	v_exp_f32_e32 v197, v197
	v_add_f32_e32 v18, v191, v18
	v_cndmask_b32_e32 v195, 0, v193, vcc
	v_cmp_lt_f32_e32 vcc, s59, v57
	v_add_f32_e32 v18, v195, v18
	v_add_f32_e32 v18, v190, v18
	v_cndmask_b32_e32 v193, 0, v215, vcc
	v_cmp_lt_f32_e32 vcc, s59, v63
	v_add_f32_e32 v18, v192, v18
	s_nop 0
	v_cndmask_b32_e32 v194, 0, v196, vcc
	v_cmp_lt_f32_e32 vcc, s59, v56
	v_add_f32_e32 v18, v194, v18
	s_nop 0
	v_cndmask_b32_e32 v196, 0, v216, vcc
	v_cmp_lt_f32_e32 vcc, s59, v62
	s_nop 1
	v_cndmask_b32_e32 v197, 0, v197, vcc
	v_cmp_lt_f32_e32 vcc, s59, v177
	v_add_f32_e32 v18, v197, v18
	v_add_f32_e32 v18, v193, v18
	v_cndmask_b32_e32 v182, 0, v219, vcc
	v_cmp_lt_f32_e32 vcc, s59, v59
	v_add_f32_e32 v18, v196, v18
	s_nop 0
	v_cndmask_b32_e32 v183, 0, v217, vcc
	v_cmp_lt_f32_e32 vcc, s59, v53
	v_add_f32_e32 v18, v183, v18
	s_nop 0
	v_cndmask_b32_e32 v184, 0, v220, vcc
	v_cmp_lt_f32_e32 vcc, s59, v58
	s_nop 1
	v_cndmask_b32_e32 v187, 0, v218, vcc
	v_cmp_lt_f32_e32 vcc, s59, v49
	v_add_f32_e32 v18, v187, v18
	v_add_f32_e32 v18, v182, v18
	v_cndmask_b32_e32 v185, 0, v223, vcc
	v_cmp_lt_f32_e32 vcc, s59, v55
	v_add_f32_e32 v18, v184, v18
	s_nop 0
	v_cndmask_b32_e32 v186, 0, v221, vcc
	v_cmp_lt_f32_e32 vcc, s59, v48
	v_add_f32_e32 v18, v186, v18
	s_nop 0
	v_cndmask_b32_e32 v188, 0, v224, vcc
	v_cmp_lt_f32_e32 vcc, s59, v54
	s_nop 1
	v_cndmask_b32_e32 v189, 0, v222, vcc
	v_cmp_lt_f32_e32 vcc, s59, v45
	v_add_f32_e32 v18, v189, v18
	v_add_f32_e32 v18, v185, v18
	v_cndmask_b32_e32 v79, 0, v227, vcc
	v_cmp_lt_f32_e32 vcc, s59, v51
	v_add_f32_e32 v18, v188, v18
	s_nop 0
	v_cndmask_b32_e32 v88, 0, v225, vcc
	v_cmp_lt_f32_e32 vcc, s59, v44
	v_add_f32_e32 v18, v88, v18
	s_nop 0
	v_cndmask_b32_e32 v95, 0, v228, vcc
	v_cmp_lt_f32_e32 vcc, s59, v50
	s_nop 1
	v_cndmask_b32_e32 v179, 0, v226, vcc
	v_cmp_lt_f32_e32 vcc, s59, v41
	v_add_f32_e32 v18, v179, v18
	v_add_f32_e32 v18, v79, v18
	v_cndmask_b32_e32 v177, 0, v231, vcc
	v_cmp_lt_f32_e32 vcc, s59, v47
	v_add_f32_e32 v18, v95, v18
	s_nop 0
	v_cndmask_b32_e32 v178, 0, v229, vcc
	v_cmp_lt_f32_e32 vcc, s59, v40
	v_add_f32_e32 v18, v178, v18
	s_nop 0
	v_cndmask_b32_e32 v180, 0, v232, vcc
	v_cmp_lt_f32_e32 vcc, s59, v46
	s_nop 1
	v_cndmask_b32_e32 v181, 0, v230, vcc
	v_cmp_lt_f32_e32 vcc, s59, v37
	v_add_f32_e32 v18, v181, v18
	v_add_f32_e32 v18, v177, v18
	v_cndmask_b32_e32 v71, 0, v235, vcc
	v_cmp_lt_f32_e32 vcc, s59, v43
	v_add_f32_e32 v18, v180, v18
	s_nop 0
	v_cndmask_b32_e32 v72, 0, v233, vcc
	v_cmp_lt_f32_e32 vcc, s59, v36
	v_add_f32_e32 v18, v72, v18
	s_nop 0
	v_cndmask_b32_e32 v73, 0, v236, vcc
	v_cmp_lt_f32_e32 vcc, s59, v42
	s_nop 1
	v_cndmask_b32_e32 v76, 0, v234, vcc
	v_cmp_lt_f32_e32 vcc, s59, v33
	v_add_f32_e32 v18, v76, v18
	v_add_f32_e32 v18, v71, v18
	v_cndmask_b32_e32 v74, 0, v239, vcc
	v_cmp_lt_f32_e32 vcc, s59, v39
	v_add_f32_e32 v18, v73, v18
	s_nop 0
	v_cndmask_b32_e32 v75, 0, v237, vcc
	v_cmp_lt_f32_e32 vcc, s59, v32
	v_add_f32_e32 v18, v75, v18
	s_nop 0
	v_cndmask_b32_e32 v77, 0, v240, vcc
	v_cmp_lt_f32_e32 vcc, s59, v38
	s_nop 1
	v_cndmask_b32_e32 v78, 0, v238, vcc
	v_cmp_lt_f32_e32 vcc, s59, v29
	v_add_f32_e32 v18, v78, v18
	v_add_f32_e32 v18, v74, v18
	v_cndmask_b32_e32 v63, 0, v243, vcc
	v_cmp_lt_f32_e32 vcc, s59, v35
	v_add_f32_e32 v18, v77, v18
	s_nop 0
	v_cndmask_b32_e32 v64, 0, v241, vcc
	v_cmp_lt_f32_e32 vcc, s59, v28
	v_add_f32_e32 v18, v64, v18
	s_nop 0
	v_cndmask_b32_e32 v65, 0, v244, vcc
	v_cmp_lt_f32_e32 vcc, s59, v34
	s_nop 1
	v_cndmask_b32_e32 v68, 0, v242, vcc
	v_cmp_lt_f32_e32 vcc, s59, v25
	v_add_f32_e32 v18, v68, v18
	v_add_f32_e32 v18, v63, v18
	v_cndmask_b32_e32 v66, 0, v247, vcc
	v_cmp_lt_f32_e32 vcc, s59, v31
	v_add_f32_e32 v18, v65, v18
	s_nop 0
	v_cndmask_b32_e32 v67, 0, v245, vcc
	v_cmp_lt_f32_e32 vcc, s59, v24
	v_add_f32_e32 v18, v67, v18
	s_nop 0
	v_cndmask_b32_e32 v69, 0, v248, vcc
	v_cmp_lt_f32_e32 vcc, s59, v30
	s_nop 1
	v_cndmask_b32_e32 v70, 0, v246, vcc
	v_cmp_lt_f32_e32 vcc, s59, v21
	v_add_f32_e32 v18, v70, v18
	v_add_f32_e32 v18, v66, v18
	v_cndmask_b32_e32 v55, 0, v251, vcc
	v_cmp_lt_f32_e32 vcc, s59, v27
	v_add_f32_e32 v18, v69, v18
	s_nop 0
	v_cndmask_b32_e32 v56, 0, v249, vcc
	v_cmp_lt_f32_e32 vcc, s59, v20
	v_add_f32_e32 v18, v56, v18
	s_nop 0
	v_cndmask_b32_e32 v57, 0, v252, vcc
	v_cmp_lt_f32_e32 vcc, s59, v26
	s_nop 1
	v_cndmask_b32_e32 v60, 0, v250, vcc
	v_cmp_lt_f32_e32 vcc, s59, v17
	v_add_f32_e32 v18, v60, v18
	v_add_f32_e32 v18, v55, v18
	v_cndmask_b32_e32 v58, 0, v135, vcc
	v_cmp_lt_f32_e32 vcc, s59, v23
	v_add_f32_e32 v18, v57, v18
	s_nop 0
	v_cndmask_b32_e32 v59, 0, v253, vcc
	v_cmp_lt_f32_e32 vcc, s59, v16
	v_add_f32_e32 v16, v59, v18
	s_nop 0
	v_cndmask_b32_e32 v61, 0, v176, vcc
	v_cmp_lt_f32_e32 vcc, s59, v22
	s_nop 1
	v_cndmask_b32_e32 v62, 0, v254, vcc
	v_add_f32_e32 v16, v62, v16
	v_add_f32_e32 v16, v58, v16
	v_add_f32_e32 v16, v61, v16
	ds_bpermute_b32 v17, v19, v16
	s_and_b64 vcc, exec, s[12:13]
	s_waitcnt lgkmcnt(0)
	v_add_f32_e32 v53, v16, v17
	ds_bpermute_b32 v54, v214, v53
